# packed-f32 SwiGLU epilogue (bit-identical), 64-bit acc zeroing, counted vmcnt waits, rglru ssq-sum batching
# speedup vs baseline: 1.0138x; 1.0138x over previous
;   __device__ __forceinline__ bool next(int i,AttnUnit&u)const{ if(i>=4)return false; const int s=(vcu&1)*2; u.bh=vcu>>1; u.qb=(i==0)?s:(i==1)?7-s:(i==2)?s+1:6-s; return true; }
; template <class Epi, class Sched, bool ALIGN_EPI = false, bool SP2 = false>
; __device__ __forceinline__ void gemm_phase(PG8_LAS unsigned char* lds, const Gemm g, const Sched& S, const Epi& E) {
;     ...
;         const bool has_next = S.next(ui + 1, nxt);
;         const char* nA = has_next ? (const char*)g.A + (size_t)nxt.pm * tstep : cA; const char* nB = has_next ? (const char*)g.Bt + (size_t)nxt.pn * tstep : cB;
;     ...
; #pragma unroll
;         for (int a = 0; a < 2; ++a)
; #pragma unroll
;             for (int b = 0; b < 2; ++b)
; #pragma unroll
;                 for (int m = 0; m < 4; ++m)
; #pragma unroll
;                     for (int n = 0; n < 2; ++n) acc[a][b][m][n] = (f32x4){0.f, 0.f, 0.f, 0.f};
;         cur = nxt; cA = nA; cB = nB; ++ui;
.LBB0_120:
	s_ashr_i32 s13, s12, 31
	s_lshl_b64 s[16:17], s[12:13], 19
	s_add_u32 s16, s28, s16
	s_addc_u32 s17, s29, s17
	s_and_b64 s[18:19], s[2:3], exec
	s_cselect_b32 s13, s17, s21
	s_cselect_b32 s52, s16, s20
	s_ashr_i32 s15, s14, 31
	s_lshl_b64 s[18:19], s[14:15], 19
	s_add_u32 s18, s30, s18
	s_addc_u32 s19, s31, s19
	s_and_b64 s[24:25], s[2:3], exec
	s_cselect_b32 s15, s19, s23
	s_cselect_b32 s53, s18, s22
	s_add_u32 s20, s20, 0x40080
	s_addc_u32 s21, s21, 0
	s_add_u32 s62, s22, 0x100
	v_mov_b64_e32 v[18:19], 0
	v_mov_b64_e32 v[20:21], 0
	v_mov_b64_e32 v[22:23], 0
	v_mov_b64_e32 v[24:25], 0
	v_mov_b64_e32 v[26:27], 0
	v_mov_b64_e32 v[28:29], 0
	v_mov_b64_e32 v[30:31], 0
	v_mov_b64_e32 v[32:33], 0
	v_mov_b64_e32 v[34:35], 0
	v_mov_b64_e32 v[36:37], 0
	v_mov_b64_e32 v[38:39], 0
	v_mov_b64_e32 v[40:41], 0
	v_mov_b64_e32 v[42:43], 0
	v_mov_b64_e32 v[44:45], 0
	v_mov_b64_e32 v[46:47], 0
	v_mov_b64_e32 v[48:49], 0
	v_mov_b64_e32 v[50:51], 0
	v_mov_b64_e32 v[52:53], 0
	v_mov_b64_e32 v[54:55], 0
	v_mov_b64_e32 v[56:57], 0
	v_mov_b64_e32 v[58:59], 0
	v_mov_b64_e32 v[60:61], 0
	v_mov_b64_e32 v[62:63], 0
	v_mov_b64_e32 v[64:65], 0
	v_mov_b64_e32 v[66:67], 0
	v_mov_b64_e32 v[68:69], 0
	v_mov_b64_e32 v[70:71], 0
	v_mov_b64_e32 v[72:73], 0
	v_mov_b64_e32 v[74:75], 0
	v_mov_b64_e32 v[76:77], 0
	v_mov_b64_e32 v[78:79], 0
	v_mov_b64_e32 v[80:81], 0
	v_mov_b64_e32 v[82:83], 0
	v_mov_b64_e32 v[84:85], 0
	v_mov_b64_e32 v[86:87], 0
	v_mov_b64_e32 v[88:89], 0
	v_mov_b64_e32 v[90:91], 0
	v_mov_b64_e32 v[92:93], 0
	v_mov_b64_e32 v[94:95], 0
	v_mov_b64_e32 v[96:97], 0
	v_mov_b64_e32 v[98:99], 0
	v_mov_b64_e32 v[100:101], 0
	v_mov_b64_e32 v[102:103], 0
	v_mov_b64_e32 v[104:105], 0
	v_mov_b64_e32 v[106:107], 0
	v_mov_b64_e32 v[108:109], 0
	v_mov_b64_e32 v[110:111], 0
	v_mov_b64_e32 v[112:113], 0
	v_mov_b64_e32 v[114:115], 0
	v_mov_b64_e32 v[116:117], 0
	v_mov_b64_e32 v[118:119], 0
	v_mov_b64_e32 v[120:121], 0
	v_mov_b64_e32 v[122:123], 0
	v_mov_b64_e32 v[124:125], 0
	v_mov_b64_e32 v[126:127], 0
	v_mov_b64_e32 v[128:129], 0
	v_mov_b64_e32 v[130:131], 0
	v_mov_b64_e32 v[132:133], 0
	v_mov_b64_e32 v[134:135], 0
	v_mov_b64_e32 v[136:137], 0
	v_mov_b64_e32 v[138:139], 0
	v_mov_b64_e32 v[140:141], 0
	v_mov_b64_e32 v[142:143], 0
	v_mov_b64_e32 v[144:145], 0
	s_addc_u32 s63, s23, 0
	s_mov_b32 s64, -2

; __device__ __forceinline__ unsigned cvt_pk_bf16(float lo, float hi) { unsigned r; asm volatile("v_cvt_pk_bf16_f32 %0, %1, %2" : "=v"(r) : "v"(lo), "v"(hi)); return r; }
; __device__ __forceinline__ float silu_f(float g) { return g * __builtin_amdgcn_rcpf(1.0f + __expf(-g)); }
;     __device__ __forceinline__ void operator()(const f32x4 (&acc)[2][2][4][2], const Unit& u, int ui, int wr, int wc, int fr, int fq) const {
;         const int row0 = u.pm * BM + wr * 64 + fr, col0 = u.pn * HALF + wc * 32 + 8 * fq;
; #pragma unroll
;         for (int ai = 0; ai < 2; ++ai)
; #pragma unroll
;             for (int m = 0; m < 4; ++m) {
;                 const int row = row0 + ai * HALF + m * 16;
;                 const float s = rsb[(ui & 1) * 256 + ai * HALF + wr * 64 + m * 16 + fr];
;                 f32x4 g0 = acc[ai][0][m][0] * s, g1 = acc[ai][0][m][1] * s, u0 = acc[ai][1][m][0] * s, u1 = acc[ai][1][m][1] * s;
;                 u32x4 w;
;                 w.x = cvt_pk_bf16(silu_f(g0[0]) * u0[0], silu_f(g0[1]) * u0[1]); w.y = cvt_pk_bf16(silu_f(g0[2]) * u0[2], silu_f(g0[3]) * u0[3]);
;                 w.z = cvt_pk_bf16(silu_f(g1[0]) * u1[0], silu_f(g1[1]) * u1[1]); w.w = cvt_pk_bf16(silu_f(g1[2]) * u1[2], silu_f(g1[3]) * u1[3]);
;                 *(u32x4*)(H + (size_t)row * ldh + col0) = w;
.LBB0_128:
	s_lshl_b32 s2, s61, 10
	s_and_b32 s2, s2, 0x400
	v_add_u32_e32 v165, s2, v162
	ds_read_b32 v176, v165
	ds_read_b32 v178, v165 offset:64
	ds_read_b32 v180, v165 offset:128
	ds_read_b32 v182, v165 offset:192
	ds_read_b32 v184, v165 offset:512
	ds_read_b32 v186, v165 offset:576
	ds_read_b32 v188, v165 offset:640
	ds_read_b32 v190, v165 offset:704
	v_lshl_or_b32 v158, s45, 7, v161
	v_lshl_add_u32 v164, s44, 8, v1
	v_ashrrev_i32_e32 v159, 31, v158
	s_mov_b32 s98, 0x16000
	s_mov_b32 s99, 0
	s_mov_b32 s100, 0x6e000
	s_mov_b32 s101, 0
	v_mov_b32_e32 v172, 0xbfb8aa3b
	v_mov_b32_e32 v174, 1.0
	v_mov_b64_e32 v[166:167], s[8:9]
	v_mad_i64_i32 v[192:193], s[2:3], v164, s71, v[166:167]
	v_lshlrev_b64 v[166:167], 1, v[158:159]
	v_lshl_add_u64 v[192:193], v[192:193], 0, v[166:167]
	s_waitcnt lgkmcnt(0)
	v_pk_mul_f32 v[142:143], v[142:143], v[176:177] op_sel_hi:[1,0]
	v_pk_mul_f32 v[144:145], v[144:145], v[176:177] op_sel_hi:[1,0]
	v_pk_mul_f32 v[138:139], v[138:139], v[176:177] op_sel_hi:[1,0]
	v_pk_mul_f32 v[140:141], v[140:141], v[176:177] op_sel_hi:[1,0]
	v_pk_mul_f32 v[134:135], v[134:135], v[176:177] op_sel_hi:[1,0]
	v_pk_mul_f32 v[136:137], v[136:137], v[176:177] op_sel_hi:[1,0]
	v_pk_mul_f32 v[130:131], v[130:131], v[176:177] op_sel_hi:[1,0]
	v_pk_mul_f32 v[132:133], v[132:133], v[176:177] op_sel_hi:[1,0]
	v_pk_mul_f32 v[168:169], v[142:143], v[172:173] op_sel_hi:[1,0]
	v_pk_mul_f32 v[170:171], v[144:145], v[172:173] op_sel_hi:[1,0]
	v_exp_f32_e32 v168, v168
	v_exp_f32_e32 v169, v169
	v_exp_f32_e32 v170, v170
	v_exp_f32_e32 v171, v171
	v_pk_add_f32 v[168:169], v[168:169], v[174:175] op_sel_hi:[1,0]
	v_pk_add_f32 v[170:171], v[170:171], v[174:175] op_sel_hi:[1,0]
	v_rcp_f32_e32 v168, v168
	v_rcp_f32_e32 v169, v169
	v_rcp_f32_e32 v170, v170
	v_rcp_f32_e32 v171, v171
	v_pk_mul_f32 v[142:143], v[142:143], v[168:169]
	v_pk_mul_f32 v[144:145], v[144:145], v[170:171]
	v_pk_mul_f32 v[134:135], v[134:135], v[142:143]
	v_pk_mul_f32 v[136:137], v[136:137], v[144:145]
	v_cvt_pk_bf16_f32 v134, v134, v135
	v_cvt_pk_bf16_f32 v135, v136, v137
	v_pk_mul_f32 v[168:169], v[138:139], v[172:173] op_sel_hi:[1,0]
	v_pk_mul_f32 v[170:171], v[140:141], v[172:173] op_sel_hi:[1,0]
	v_exp_f32_e32 v168, v168
	v_exp_f32_e32 v169, v169
	v_exp_f32_e32 v170, v170
	v_exp_f32_e32 v171, v171
	v_pk_add_f32 v[168:169], v[168:169], v[174:175] op_sel_hi:[1,0]
	v_pk_add_f32 v[170:171], v[170:171], v[174:175] op_sel_hi:[1,0]
	v_rcp_f32_e32 v168, v168
	v_rcp_f32_e32 v169, v169
	v_rcp_f32_e32 v170, v170
	v_rcp_f32_e32 v171, v171
	v_pk_mul_f32 v[138:139], v[138:139], v[168:169]
	v_pk_mul_f32 v[140:141], v[140:141], v[170:171]
	v_pk_mul_f32 v[130:131], v[130:131], v[138:139]
	v_pk_mul_f32 v[132:133], v[132:133], v[140:141]
	v_cvt_pk_bf16_f32 v136, v130, v131
	v_cvt_pk_bf16_f32 v137, v132, v133
	global_store_dwordx4 v[192:193], v[134:137], off
	v_lshl_add_u64 v[192:193], v[192:193], 0, s[98:99]
	v_pk_mul_f32 v[126:127], v[126:127], v[178:179] op_sel_hi:[1,0]
	v_pk_mul_f32 v[128:129], v[128:129], v[178:179] op_sel_hi:[1,0]
	v_pk_mul_f32 v[122:123], v[122:123], v[178:179] op_sel_hi:[1,0]
	v_pk_mul_f32 v[124:125], v[124:125], v[178:179] op_sel_hi:[1,0]
	v_pk_mul_f32 v[118:119], v[118:119], v[178:179] op_sel_hi:[1,0]
	v_pk_mul_f32 v[120:121], v[120:121], v[178:179] op_sel_hi:[1,0]
	v_pk_mul_f32 v[114:115], v[114:115], v[178:179] op_sel_hi:[1,0]
	v_pk_mul_f32 v[116:117], v[116:117], v[178:179] op_sel_hi:[1,0]
	v_pk_mul_f32 v[168:169], v[126:127], v[172:173] op_sel_hi:[1,0]
	v_pk_mul_f32 v[170:171], v[128:129], v[172:173] op_sel_hi:[1,0]
	v_exp_f32_e32 v168, v168
	v_exp_f32_e32 v169, v169
	v_exp_f32_e32 v170, v170
	v_exp_f32_e32 v171, v171
	v_pk_add_f32 v[168:169], v[168:169], v[174:175] op_sel_hi:[1,0]
	v_pk_add_f32 v[170:171], v[170:171], v[174:175] op_sel_hi:[1,0]
	v_rcp_f32_e32 v168, v168
	v_rcp_f32_e32 v169, v169
	v_rcp_f32_e32 v170, v170
	v_rcp_f32_e32 v171, v171
	v_pk_mul_f32 v[126:127], v[126:127], v[168:169]
	v_pk_mul_f32 v[128:129], v[128:129], v[170:171]
	v_pk_mul_f32 v[118:119], v[118:119], v[126:127]
	v_pk_mul_f32 v[120:121], v[120:121], v[128:129]
	v_cvt_pk_bf16_f32 v118, v118, v119
	v_cvt_pk_bf16_f32 v119, v120, v121
	v_pk_mul_f32 v[168:169], v[122:123], v[172:173] op_sel_hi:[1,0]
	v_pk_mul_f32 v[170:171], v[124:125], v[172:173] op_sel_hi:[1,0]
	v_exp_f32_e32 v168, v168
	v_exp_f32_e32 v169, v169
	v_exp_f32_e32 v170, v170
	v_exp_f32_e32 v171, v171
	v_pk_add_f32 v[168:169], v[168:169], v[174:175] op_sel_hi:[1,0]
	v_pk_add_f32 v[170:171], v[170:171], v[174:175] op_sel_hi:[1,0]
	v_rcp_f32_e32 v168, v168
	v_rcp_f32_e32 v169, v169
	v_rcp_f32_e32 v170, v170
	v_rcp_f32_e32 v171, v171
	v_pk_mul_f32 v[122:123], v[122:123], v[168:169]
	v_pk_mul_f32 v[124:125], v[124:125], v[170:171]
	v_pk_mul_f32 v[114:115], v[114:115], v[122:123]
	v_pk_mul_f32 v[116:117], v[116:117], v[124:125]
	v_cvt_pk_bf16_f32 v120, v114, v115
	v_cvt_pk_bf16_f32 v121, v116, v117
	global_store_dwordx4 v[192:193], v[118:121], off
	v_lshl_add_u64 v[192:193], v[192:193], 0, s[98:99]
	v_pk_mul_f32 v[110:111], v[110:111], v[180:181] op_sel_hi:[1,0]
	v_pk_mul_f32 v[112:113], v[112:113], v[180:181] op_sel_hi:[1,0]
	v_pk_mul_f32 v[106:107], v[106:107], v[180:181] op_sel_hi:[1,0]
	v_pk_mul_f32 v[108:109], v[108:109], v[180:181] op_sel_hi:[1,0]
	v_pk_mul_f32 v[102:103], v[102:103], v[180:181] op_sel_hi:[1,0]
	v_pk_mul_f32 v[104:105], v[104:105], v[180:181] op_sel_hi:[1,0]
	v_pk_mul_f32 v[98:99], v[98:99], v[180:181] op_sel_hi:[1,0]
	v_pk_mul_f32 v[100:101], v[100:101], v[180:181] op_sel_hi:[1,0]
	v_pk_mul_f32 v[168:169], v[110:111], v[172:173] op_sel_hi:[1,0]
	v_pk_mul_f32 v[170:171], v[112:113], v[172:173] op_sel_hi:[1,0]
; __device__ __forceinline__ unsigned cvt_pk_bf16(float lo, float hi) { unsigned r; asm volatile("v_cvt_pk_bf16_f32 %0, %1, %2" : "=v"(r) : "v"(lo), "v"(hi)); return r; }
; __device__ __forceinline__ float silu_f(float g) { return g * __builtin_amdgcn_rcpf(1.0f + __expf(-g)); }
;     __device__ __forceinline__ void operator()(const f32x4 (&acc)[2][2][4][2], const Unit& u, int ui, int wr, int wc, int fr, int fq) const {
;     ...
;             for (int m = 0; m < 4; ++m) {
;                 const int row = row0 + ai * HALF + m * 16;
;                 const float s = rsb[(ui & 1) * 256 + ai * HALF + wr * 64 + m * 16 + fr];
;                 f32x4 g0 = acc[ai][0][m][0] * s, g1 = acc[ai][0][m][1] * s, u0 = acc[ai][1][m][0] * s, u1 = acc[ai][1][m][1] * s;
;                 u32x4 w;
;                 w.x = cvt_pk_bf16(silu_f(g0[0]) * u0[0], silu_f(g0[1]) * u0[1]); w.y = cvt_pk_bf16(silu_f(g0[2]) * u0[2], silu_f(g0[3]) * u0[3]);
;                 w.z = cvt_pk_bf16(silu_f(g1[0]) * u1[0], silu_f(g1[1]) * u1[1]); w.w = cvt_pk_bf16(silu_f(g1[2]) * u1[2], silu_f(g1[3]) * u1[3]);
;                 *(u32x4*)(H + (size_t)row * ldh + col0) = w;
	v_exp_f32_e32 v168, v168
	v_exp_f32_e32 v169, v169
	v_exp_f32_e32 v170, v170
	v_exp_f32_e32 v171, v171
	v_pk_add_f32 v[168:169], v[168:169], v[174:175] op_sel_hi:[1,0]
	v_pk_add_f32 v[170:171], v[170:171], v[174:175] op_sel_hi:[1,0]
	v_rcp_f32_e32 v168, v168
	v_rcp_f32_e32 v169, v169
	v_rcp_f32_e32 v170, v170
	v_rcp_f32_e32 v171, v171
	v_pk_mul_f32 v[110:111], v[110:111], v[168:169]
	v_pk_mul_f32 v[112:113], v[112:113], v[170:171]
	v_pk_mul_f32 v[102:103], v[102:103], v[110:111]
	v_pk_mul_f32 v[104:105], v[104:105], v[112:113]
	v_cvt_pk_bf16_f32 v102, v102, v103
	v_cvt_pk_bf16_f32 v103, v104, v105
	v_pk_mul_f32 v[168:169], v[106:107], v[172:173] op_sel_hi:[1,0]
	v_pk_mul_f32 v[170:171], v[108:109], v[172:173] op_sel_hi:[1,0]
	v_exp_f32_e32 v168, v168
	v_exp_f32_e32 v169, v169
	v_exp_f32_e32 v170, v170
	v_exp_f32_e32 v171, v171
	v_pk_add_f32 v[168:169], v[168:169], v[174:175] op_sel_hi:[1,0]
	v_pk_add_f32 v[170:171], v[170:171], v[174:175] op_sel_hi:[1,0]
	v_rcp_f32_e32 v168, v168
	v_rcp_f32_e32 v169, v169
	v_rcp_f32_e32 v170, v170
	v_rcp_f32_e32 v171, v171
	v_pk_mul_f32 v[106:107], v[106:107], v[168:169]
	v_pk_mul_f32 v[108:109], v[108:109], v[170:171]
	v_pk_mul_f32 v[98:99], v[98:99], v[106:107]
	v_pk_mul_f32 v[100:101], v[100:101], v[108:109]
	v_cvt_pk_bf16_f32 v104, v98, v99
	v_cvt_pk_bf16_f32 v105, v100, v101
	global_store_dwordx4 v[192:193], v[102:105], off
	v_lshl_add_u64 v[192:193], v[192:193], 0, s[98:99]
	v_pk_mul_f32 v[94:95], v[94:95], v[182:183] op_sel_hi:[1,0]
	v_pk_mul_f32 v[96:97], v[96:97], v[182:183] op_sel_hi:[1,0]
	v_pk_mul_f32 v[90:91], v[90:91], v[182:183] op_sel_hi:[1,0]
	v_pk_mul_f32 v[92:93], v[92:93], v[182:183] op_sel_hi:[1,0]
	v_pk_mul_f32 v[86:87], v[86:87], v[182:183] op_sel_hi:[1,0]
	v_pk_mul_f32 v[88:89], v[88:89], v[182:183] op_sel_hi:[1,0]
	v_pk_mul_f32 v[82:83], v[82:83], v[182:183] op_sel_hi:[1,0]
	v_pk_mul_f32 v[84:85], v[84:85], v[182:183] op_sel_hi:[1,0]
	v_pk_mul_f32 v[168:169], v[94:95], v[172:173] op_sel_hi:[1,0]
	v_pk_mul_f32 v[170:171], v[96:97], v[172:173] op_sel_hi:[1,0]
	v_exp_f32_e32 v168, v168
	v_exp_f32_e32 v169, v169
	v_exp_f32_e32 v170, v170
	v_exp_f32_e32 v171, v171
	v_pk_add_f32 v[168:169], v[168:169], v[174:175] op_sel_hi:[1,0]
	v_pk_add_f32 v[170:171], v[170:171], v[174:175] op_sel_hi:[1,0]
	v_rcp_f32_e32 v168, v168
	v_rcp_f32_e32 v169, v169
	v_rcp_f32_e32 v170, v170
	v_rcp_f32_e32 v171, v171
	v_pk_mul_f32 v[94:95], v[94:95], v[168:169]
	v_pk_mul_f32 v[96:97], v[96:97], v[170:171]
	v_pk_mul_f32 v[86:87], v[86:87], v[94:95]
	v_pk_mul_f32 v[88:89], v[88:89], v[96:97]
	v_cvt_pk_bf16_f32 v86, v86, v87
	v_cvt_pk_bf16_f32 v87, v88, v89
	v_pk_mul_f32 v[168:169], v[90:91], v[172:173] op_sel_hi:[1,0]
	v_pk_mul_f32 v[170:171], v[92:93], v[172:173] op_sel_hi:[1,0]
	v_exp_f32_e32 v168, v168
	v_exp_f32_e32 v169, v169
	v_exp_f32_e32 v170, v170
	v_exp_f32_e32 v171, v171
	v_pk_add_f32 v[168:169], v[168:169], v[174:175] op_sel_hi:[1,0]
	v_pk_add_f32 v[170:171], v[170:171], v[174:175] op_sel_hi:[1,0]
	v_rcp_f32_e32 v168, v168
	v_rcp_f32_e32 v169, v169
	v_rcp_f32_e32 v170, v170
	v_rcp_f32_e32 v171, v171
	v_pk_mul_f32 v[90:91], v[90:91], v[168:169]
	v_pk_mul_f32 v[92:93], v[92:93], v[170:171]
	v_pk_mul_f32 v[82:83], v[82:83], v[90:91]
	v_pk_mul_f32 v[84:85], v[84:85], v[92:93]
	v_cvt_pk_bf16_f32 v88, v82, v83
	v_cvt_pk_bf16_f32 v89, v84, v85
	global_store_dwordx4 v[192:193], v[86:89], off
	v_lshl_add_u64 v[192:193], v[192:193], 0, s[100:101]
	v_pk_mul_f32 v[78:79], v[78:79], v[184:185] op_sel_hi:[1,0]
	v_pk_mul_f32 v[80:81], v[80:81], v[184:185] op_sel_hi:[1,0]
	v_pk_mul_f32 v[74:75], v[74:75], v[184:185] op_sel_hi:[1,0]
	v_pk_mul_f32 v[76:77], v[76:77], v[184:185] op_sel_hi:[1,0]
	v_pk_mul_f32 v[70:71], v[70:71], v[184:185] op_sel_hi:[1,0]
	v_pk_mul_f32 v[72:73], v[72:73], v[184:185] op_sel_hi:[1,0]
	v_pk_mul_f32 v[66:67], v[66:67], v[184:185] op_sel_hi:[1,0]
	v_pk_mul_f32 v[68:69], v[68:69], v[184:185] op_sel_hi:[1,0]
	v_pk_mul_f32 v[168:169], v[78:79], v[172:173] op_sel_hi:[1,0]
	v_pk_mul_f32 v[170:171], v[80:81], v[172:173] op_sel_hi:[1,0]
	v_exp_f32_e32 v168, v168
	v_exp_f32_e32 v169, v169
	v_exp_f32_e32 v170, v170
	v_exp_f32_e32 v171, v171
	v_pk_add_f32 v[168:169], v[168:169], v[174:175] op_sel_hi:[1,0]
	v_pk_add_f32 v[170:171], v[170:171], v[174:175] op_sel_hi:[1,0]
	v_rcp_f32_e32 v168, v168
	v_rcp_f32_e32 v169, v169
	v_rcp_f32_e32 v170, v170
	v_rcp_f32_e32 v171, v171
	v_pk_mul_f32 v[78:79], v[78:79], v[168:169]
	v_pk_mul_f32 v[80:81], v[80:81], v[170:171]
	v_pk_mul_f32 v[70:71], v[70:71], v[78:79]
	v_pk_mul_f32 v[72:73], v[72:73], v[80:81]
	v_cvt_pk_bf16_f32 v70, v70, v71
	v_cvt_pk_bf16_f32 v71, v72, v73
	v_pk_mul_f32 v[168:169], v[74:75], v[172:173] op_sel_hi:[1,0]
	v_pk_mul_f32 v[170:171], v[76:77], v[172:173] op_sel_hi:[1,0]
	v_exp_f32_e32 v168, v168
	v_exp_f32_e32 v169, v169
	v_exp_f32_e32 v170, v170
	v_exp_f32_e32 v171, v171
	v_pk_add_f32 v[168:169], v[168:169], v[174:175] op_sel_hi:[1,0]
	v_pk_add_f32 v[170:171], v[170:171], v[174:175] op_sel_hi:[1,0]
	v_rcp_f32_e32 v168, v168
	v_rcp_f32_e32 v169, v169
	v_rcp_f32_e32 v170, v170
	v_rcp_f32_e32 v171, v171
	v_pk_mul_f32 v[74:75], v[74:75], v[168:169]
	v_pk_mul_f32 v[76:77], v[76:77], v[170:171]
	v_pk_mul_f32 v[66:67], v[66:67], v[74:75]
	v_pk_mul_f32 v[68:69], v[68:69], v[76:77]
	v_cvt_pk_bf16_f32 v72, v66, v67
	v_cvt_pk_bf16_f32 v73, v68, v69
	global_store_dwordx4 v[192:193], v[70:73], off
	v_lshl_add_u64 v[192:193], v[192:193], 0, s[98:99]
	v_pk_mul_f32 v[62:63], v[62:63], v[186:187] op_sel_hi:[1,0]
	v_pk_mul_f32 v[64:65], v[64:65], v[186:187] op_sel_hi:[1,0]
	v_pk_mul_f32 v[58:59], v[58:59], v[186:187] op_sel_hi:[1,0]
; __device__ __forceinline__ unsigned cvt_pk_bf16(float lo, float hi) { unsigned r; asm volatile("v_cvt_pk_bf16_f32 %0, %1, %2" : "=v"(r) : "v"(lo), "v"(hi)); return r; }
; __device__ __forceinline__ float silu_f(float g) { return g * __builtin_amdgcn_rcpf(1.0f + __expf(-g)); }
;     __device__ __forceinline__ void operator()(const f32x4 (&acc)[2][2][4][2], const Unit& u, int ui, int wr, int wc, int fr, int fq) const {
;     ...
;             for (int m = 0; m < 4; ++m) {
;                 const int row = row0 + ai * HALF + m * 16;
;                 const float s = rsb[(ui & 1) * 256 + ai * HALF + wr * 64 + m * 16 + fr];
;                 f32x4 g0 = acc[ai][0][m][0] * s, g1 = acc[ai][0][m][1] * s, u0 = acc[ai][1][m][0] * s, u1 = acc[ai][1][m][1] * s;
;                 u32x4 w;
;                 w.x = cvt_pk_bf16(silu_f(g0[0]) * u0[0], silu_f(g0[1]) * u0[1]); w.y = cvt_pk_bf16(silu_f(g0[2]) * u0[2], silu_f(g0[3]) * u0[3]);
;                 w.z = cvt_pk_bf16(silu_f(g1[0]) * u1[0], silu_f(g1[1]) * u1[1]); w.w = cvt_pk_bf16(silu_f(g1[2]) * u1[2], silu_f(g1[3]) * u1[3]);
;                 *(u32x4*)(H + (size_t)row * ldh + col0) = w;
; template <class Epi, class Sched, bool ALIGN_EPI = false, bool SP2 = false>
; __device__ __forceinline__ void gemm_phase(PG8_LAS unsigned char* lds, const Gemm g, const Sched& S, const Epi& E) {
;     ...
;         if constexpr (!Epi::AFTER_DRAIN) { typename Sched::Pre pre; if (has_next) S.issue(nxt, pre); E(acc, cur, ui, wr, wc, fr, fq); if (has_next) S.commit(nxt, ui + 1, pre); S.done(cur); }
;         if (!has_next) break;
	v_pk_mul_f32 v[60:61], v[60:61], v[186:187] op_sel_hi:[1,0]
	v_pk_mul_f32 v[54:55], v[54:55], v[186:187] op_sel_hi:[1,0]
	v_pk_mul_f32 v[56:57], v[56:57], v[186:187] op_sel_hi:[1,0]
	v_pk_mul_f32 v[50:51], v[50:51], v[186:187] op_sel_hi:[1,0]
	v_pk_mul_f32 v[52:53], v[52:53], v[186:187] op_sel_hi:[1,0]
	v_pk_mul_f32 v[168:169], v[62:63], v[172:173] op_sel_hi:[1,0]
	v_pk_mul_f32 v[170:171], v[64:65], v[172:173] op_sel_hi:[1,0]
	v_exp_f32_e32 v168, v168
	v_exp_f32_e32 v169, v169
	v_exp_f32_e32 v170, v170
	v_exp_f32_e32 v171, v171
	v_pk_add_f32 v[168:169], v[168:169], v[174:175] op_sel_hi:[1,0]
	v_pk_add_f32 v[170:171], v[170:171], v[174:175] op_sel_hi:[1,0]
	v_rcp_f32_e32 v168, v168
	v_rcp_f32_e32 v169, v169
	v_rcp_f32_e32 v170, v170
	v_rcp_f32_e32 v171, v171
	v_pk_mul_f32 v[62:63], v[62:63], v[168:169]
	v_pk_mul_f32 v[64:65], v[64:65], v[170:171]
	v_pk_mul_f32 v[54:55], v[54:55], v[62:63]
	v_pk_mul_f32 v[56:57], v[56:57], v[64:65]
	v_cvt_pk_bf16_f32 v54, v54, v55
	v_cvt_pk_bf16_f32 v55, v56, v57
	v_pk_mul_f32 v[168:169], v[58:59], v[172:173] op_sel_hi:[1,0]
	v_pk_mul_f32 v[170:171], v[60:61], v[172:173] op_sel_hi:[1,0]
	v_exp_f32_e32 v168, v168
	v_exp_f32_e32 v169, v169
	v_exp_f32_e32 v170, v170
	v_exp_f32_e32 v171, v171
	v_pk_add_f32 v[168:169], v[168:169], v[174:175] op_sel_hi:[1,0]
	v_pk_add_f32 v[170:171], v[170:171], v[174:175] op_sel_hi:[1,0]
	v_rcp_f32_e32 v168, v168
	v_rcp_f32_e32 v169, v169
	v_rcp_f32_e32 v170, v170
	v_rcp_f32_e32 v171, v171
	v_pk_mul_f32 v[58:59], v[58:59], v[168:169]
	v_pk_mul_f32 v[60:61], v[60:61], v[170:171]
	v_pk_mul_f32 v[50:51], v[50:51], v[58:59]
	v_pk_mul_f32 v[52:53], v[52:53], v[60:61]
	v_cvt_pk_bf16_f32 v56, v50, v51
	v_cvt_pk_bf16_f32 v57, v52, v53
	global_store_dwordx4 v[192:193], v[54:57], off
	v_lshl_add_u64 v[192:193], v[192:193], 0, s[98:99]
	v_pk_mul_f32 v[46:47], v[46:47], v[188:189] op_sel_hi:[1,0]
	v_pk_mul_f32 v[48:49], v[48:49], v[188:189] op_sel_hi:[1,0]
	v_pk_mul_f32 v[42:43], v[42:43], v[188:189] op_sel_hi:[1,0]
	v_pk_mul_f32 v[44:45], v[44:45], v[188:189] op_sel_hi:[1,0]
	v_pk_mul_f32 v[38:39], v[38:39], v[188:189] op_sel_hi:[1,0]
	v_pk_mul_f32 v[40:41], v[40:41], v[188:189] op_sel_hi:[1,0]
	v_pk_mul_f32 v[34:35], v[34:35], v[188:189] op_sel_hi:[1,0]
	v_pk_mul_f32 v[36:37], v[36:37], v[188:189] op_sel_hi:[1,0]
	v_pk_mul_f32 v[168:169], v[46:47], v[172:173] op_sel_hi:[1,0]
	v_pk_mul_f32 v[170:171], v[48:49], v[172:173] op_sel_hi:[1,0]
	v_exp_f32_e32 v168, v168
	v_exp_f32_e32 v169, v169
	v_exp_f32_e32 v170, v170
	v_exp_f32_e32 v171, v171
	v_pk_add_f32 v[168:169], v[168:169], v[174:175] op_sel_hi:[1,0]
	v_pk_add_f32 v[170:171], v[170:171], v[174:175] op_sel_hi:[1,0]
	v_rcp_f32_e32 v168, v168
	v_rcp_f32_e32 v169, v169
	v_rcp_f32_e32 v170, v170
	v_rcp_f32_e32 v171, v171
	v_pk_mul_f32 v[46:47], v[46:47], v[168:169]
	v_pk_mul_f32 v[48:49], v[48:49], v[170:171]
	v_pk_mul_f32 v[38:39], v[38:39], v[46:47]
	v_pk_mul_f32 v[40:41], v[40:41], v[48:49]
	v_cvt_pk_bf16_f32 v38, v38, v39
	v_cvt_pk_bf16_f32 v39, v40, v41
	v_pk_mul_f32 v[168:169], v[42:43], v[172:173] op_sel_hi:[1,0]
	v_pk_mul_f32 v[170:171], v[44:45], v[172:173] op_sel_hi:[1,0]
	v_exp_f32_e32 v168, v168
	v_exp_f32_e32 v169, v169
	v_exp_f32_e32 v170, v170
	v_exp_f32_e32 v171, v171
	v_pk_add_f32 v[168:169], v[168:169], v[174:175] op_sel_hi:[1,0]
	v_pk_add_f32 v[170:171], v[170:171], v[174:175] op_sel_hi:[1,0]
	v_rcp_f32_e32 v168, v168
	v_rcp_f32_e32 v169, v169
	v_rcp_f32_e32 v170, v170
	v_rcp_f32_e32 v171, v171
	v_pk_mul_f32 v[42:43], v[42:43], v[168:169]
	v_pk_mul_f32 v[44:45], v[44:45], v[170:171]
	v_pk_mul_f32 v[34:35], v[34:35], v[42:43]
	v_pk_mul_f32 v[36:37], v[36:37], v[44:45]
	v_cvt_pk_bf16_f32 v40, v34, v35
	v_cvt_pk_bf16_f32 v41, v36, v37
	global_store_dwordx4 v[192:193], v[38:41], off
	v_lshl_add_u64 v[192:193], v[192:193], 0, s[98:99]
	v_pk_mul_f32 v[30:31], v[30:31], v[190:191] op_sel_hi:[1,0]
	v_pk_mul_f32 v[32:33], v[32:33], v[190:191] op_sel_hi:[1,0]
	v_pk_mul_f32 v[26:27], v[26:27], v[190:191] op_sel_hi:[1,0]
	v_pk_mul_f32 v[28:29], v[28:29], v[190:191] op_sel_hi:[1,0]
	v_pk_mul_f32 v[22:23], v[22:23], v[190:191] op_sel_hi:[1,0]
	v_pk_mul_f32 v[24:25], v[24:25], v[190:191] op_sel_hi:[1,0]
	v_pk_mul_f32 v[18:19], v[18:19], v[190:191] op_sel_hi:[1,0]
	v_pk_mul_f32 v[20:21], v[20:21], v[190:191] op_sel_hi:[1,0]
	v_pk_mul_f32 v[168:169], v[30:31], v[172:173] op_sel_hi:[1,0]
	v_pk_mul_f32 v[170:171], v[32:33], v[172:173] op_sel_hi:[1,0]
	v_exp_f32_e32 v168, v168
	v_exp_f32_e32 v169, v169
	v_exp_f32_e32 v170, v170
	v_exp_f32_e32 v171, v171
	v_pk_add_f32 v[168:169], v[168:169], v[174:175] op_sel_hi:[1,0]
	v_pk_add_f32 v[170:171], v[170:171], v[174:175] op_sel_hi:[1,0]
	v_rcp_f32_e32 v168, v168
	v_rcp_f32_e32 v169, v169
	v_rcp_f32_e32 v170, v170
	v_rcp_f32_e32 v171, v171
	v_pk_mul_f32 v[30:31], v[30:31], v[168:169]
	v_pk_mul_f32 v[32:33], v[32:33], v[170:171]
	v_pk_mul_f32 v[22:23], v[22:23], v[30:31]
	v_pk_mul_f32 v[24:25], v[24:25], v[32:33]
	v_cvt_pk_bf16_f32 v22, v22, v23
	v_cvt_pk_bf16_f32 v23, v24, v25
	v_pk_mul_f32 v[168:169], v[26:27], v[172:173] op_sel_hi:[1,0]
	v_pk_mul_f32 v[170:171], v[28:29], v[172:173] op_sel_hi:[1,0]
	v_exp_f32_e32 v168, v168
	v_exp_f32_e32 v169, v169
	v_exp_f32_e32 v170, v170
	v_exp_f32_e32 v171, v171
	v_pk_add_f32 v[168:169], v[168:169], v[174:175] op_sel_hi:[1,0]
	v_pk_add_f32 v[170:171], v[170:171], v[174:175] op_sel_hi:[1,0]
	v_rcp_f32_e32 v168, v168
	v_rcp_f32_e32 v169, v169
	v_rcp_f32_e32 v170, v170
	v_rcp_f32_e32 v171, v171
	v_pk_mul_f32 v[26:27], v[26:27], v[168:169]
	v_pk_mul_f32 v[28:29], v[28:29], v[170:171]
	v_pk_mul_f32 v[18:19], v[18:19], v[26:27]
	v_pk_mul_f32 v[20:21], v[20:21], v[28:29]
	v_cvt_pk_bf16_f32 v24, v18, v19
	v_cvt_pk_bf16_f32 v25, v20, v21
	s_mov_b64 s[2:3], -1
	s_cmp_eq_u32 s61, 10
	global_store_dwordx4 v[192:193], v[22:25], off
	s_cbranch_scc1 .LBB0_117
;     __device__ __forceinline__ void commit(const Unit& u, int ui, const Pre& p) const {
;         int t = threadIdx.x; asm volatile("" : "+v"(t));
;         if (t < 256) rsb[(ui & 1) * 256 + t] = fin(p.a, p.b, p.c, p.d);
;     }
	s_nop 0
	v_mov_b32_e32 v18, v204
	s_nop 0
	v_cmp_gt_i32_e32 vcc, s68, v18
	s_and_saveexec_b64 s[20:21], vcc
	s_cbranch_execz .LBB0_131
	s_waitcnt vmcnt(8)
	v_mov_b32_e32 v20, v6
	v_mov_b32_e32 v21, v14
	v_mov_b32_e32 v22, v7
	v_mov_b32_e32 v23, v15
	v_pk_add_f32 v[20:21], v[20:21], v[22:23]
	v_mov_b32_e32 v22, v8
	v_mov_b32_e32 v23, v16
	v_mov_b32_e32 v24, v9
	v_mov_b32_e32 v25, v17
	v_pk_add_f32 v[22:23], v[22:23], v[24:25]
	v_mov_b32_e32 v24, v3
	v_pk_add_f32 v[20:21], v[20:21], v[22:23]
	v_mov_b32_e32 v22, v2
	v_mov_b32_e32 v23, v10
	v_mov_b32_e32 v25, v11
	v_pk_add_f32 v[22:23], v[22:23], v[24:25]
	v_mov_b32_e32 v24, v4
	v_mov_b32_e32 v25, v12
	v_mov_b32_e32 v26, v5
	v_mov_b32_e32 v27, v13
	v_pk_add_f32 v[24:25], v[24:25], v[26:27]
	s_nop 0
	v_pk_add_f32 v[22:23], v[22:23], v[24:25]
	s_nop 0
	v_pk_add_f32 v[20:21], v[22:23], v[20:21]
	s_nop 0
	v_add_f32_e32 v19, v20, v21
	v_fmamk_f32 v19, v19, 0x3a800000, v205
	v_mul_f32_e32 v20, 0x4f800000, v19
	v_cmp_gt_f32_e32 vcc, s69, v19
	s_nop 1
	v_cndmask_b32_e32 v19, v19, v20, vcc
	v_sqrt_f32_e32 v20, v19
	s_nop 0
	v_add_u32_e32 v21, -1, v20
	v_fma_f32 v22, -v21, v20, v19
	v_cmp_ge_f32_e64 s[2:3], 0, v22
	v_add_u32_e32 v22, 1, v20
	s_nop 0
	v_cndmask_b32_e64 v21, v20, v21, s[2:3]
	v_fma_f32 v20, -v22, v20, v19
	v_cmp_lt_f32_e64 s[2:3], 0, v20
	s_nop 1
	v_cndmask_b32_e64 v20, v21, v22, s[2:3]
	v_mul_f32_e32 v21, 0x37800000, v20
	v_cndmask_b32_e32 v20, v20, v21, vcc
	v_cmp_class_f32_e32 vcc, v19, v206
	s_nop 1
	v_cndmask_b32_e32 v19, v20, v19, vcc
	v_div_scale_f32 v20, s[2:3], v19, v19, 1.0
	v_rcp_f32_e32 v21, v20
	s_lshl_b32 s2, s60, 10
	s_and_b32 s2, s2, 0x400
	s_add_i32 s2, s2, 0
	v_fma_f32 v22, -v20, v21, 1.0
	v_fmac_f32_e32 v21, v22, v21
	v_div_scale_f32 v22, vcc, 1.0, v19, 1.0
	v_mul_f32_e32 v23, v22, v21
	v_fma_f32 v24, -v20, v23, v22
	v_fmac_f32_e32 v23, v24, v21
	v_fma_f32 v20, -v20, v23, v22
	v_div_fmas_f32 v20, v20, v21, v23
	v_lshl_add_u32 v18, v18, 2, s2
	v_div_fixup_f32 v19, v20, v19, 1.0
	v_add_u32_e32 v18, 0x20400, v18
	ds_write_b32 v18, v19

; template <class Epi, class Sched, bool ALIGN_EPI = false, bool SP2 = false>
; __device__ __forceinline__ void gemm_phase(PG8_LAS unsigned char* lds, const Gemm g, const Sched& S, const Epi& E) {
;     ...
; #pragma unroll
;         for (int a = 0; a < 2; ++a)
; #pragma unroll
;             for (int b = 0; b < 2; ++b)
; #pragma unroll
;                 for (int m = 0; m < 4; ++m)
; #pragma unroll
;                     for (int n = 0; n < 2; ++n) acc[a][b][m][n] = (f32x4){0.f, 0.f, 0.f, 0.f};
;         cur = nxt; cA = nA; cB = nB; ++ui;
.LBB0_211:
	s_mov_b64 s[18:19], s[6:7]
	s_mov_b64 s[20:21], s[14:15]
	s_and_b64 s[6:7], s[16:17], exec
	s_cselect_b32 s7, s37, s19
	s_cselect_b32 s6, s36, s18
	s_cselect_b32 s15, s3, s21
	s_cselect_b32 s14, s2, s20
	s_add_u32 s39, s20, 0x100
	v_mov_b64_e32 v[2:3], 0
	v_mov_b64_e32 v[4:5], 0
	v_mov_b64_e32 v[6:7], 0
	v_mov_b64_e32 v[8:9], 0
	v_mov_b64_e32 v[10:11], 0
	v_mov_b64_e32 v[12:13], 0
	v_mov_b64_e32 v[14:15], 0
	v_mov_b64_e32 v[16:17], 0
	v_mov_b64_e32 v[18:19], 0
	v_mov_b64_e32 v[20:21], 0
	v_mov_b64_e32 v[22:23], 0
	v_mov_b64_e32 v[24:25], 0
	v_mov_b64_e32 v[26:27], 0
	v_mov_b64_e32 v[28:29], 0
	v_mov_b64_e32 v[30:31], 0
	v_mov_b64_e32 v[32:33], 0
	v_mov_b64_e32 v[34:35], 0
	v_mov_b64_e32 v[36:37], 0
	v_mov_b64_e32 v[38:39], 0
	v_mov_b64_e32 v[40:41], 0
	v_mov_b64_e32 v[42:43], 0
	v_mov_b64_e32 v[44:45], 0
	v_mov_b64_e32 v[46:47], 0
	v_mov_b64_e32 v[48:49], 0
	v_mov_b64_e32 v[50:51], 0
	v_mov_b64_e32 v[52:53], 0
	v_mov_b64_e32 v[54:55], 0
	v_mov_b64_e32 v[56:57], 0
	v_mov_b64_e32 v[58:59], 0
	v_mov_b64_e32 v[60:61], 0
	v_mov_b64_e32 v[62:63], 0
	v_mov_b64_e32 v[64:65], 0
	v_mov_b64_e32 v[66:67], 0
	v_mov_b64_e32 v[68:69], 0
	v_mov_b64_e32 v[70:71], 0
	v_mov_b64_e32 v[72:73], 0
	v_mov_b64_e32 v[74:75], 0
	v_mov_b64_e32 v[76:77], 0
	v_mov_b64_e32 v[78:79], 0
	v_mov_b64_e32 v[80:81], 0
	v_mov_b64_e32 v[82:83], 0
	v_mov_b64_e32 v[84:85], 0
	v_mov_b64_e32 v[86:87], 0
	v_mov_b64_e32 v[88:89], 0
	v_mov_b64_e32 v[90:91], 0
	v_mov_b64_e32 v[92:93], 0
	v_mov_b64_e32 v[94:95], 0
	v_mov_b64_e32 v[96:97], 0
	v_mov_b64_e32 v[98:99], 0
	v_mov_b64_e32 v[100:101], 0
	v_mov_b64_e32 v[102:103], 0
	v_mov_b64_e32 v[104:105], 0
	v_mov_b64_e32 v[106:107], 0
	v_mov_b64_e32 v[108:109], 0
	v_mov_b64_e32 v[110:111], 0
	v_mov_b64_e32 v[112:113], 0
	v_mov_b64_e32 v[114:115], 0
	v_mov_b64_e32 v[116:117], 0
	v_mov_b64_e32 v[118:119], 0
	v_mov_b64_e32 v[120:121], 0
	v_mov_b64_e32 v[122:123], 0
	v_mov_b64_e32 v[124:125], 0
	v_mov_b64_e32 v[126:127], 0
	v_mov_b64_e32 v[128:129], 0
	s_addc_u32 s42, s21, 0
	s_mov_b32 s44, -2

; template <class Epi, class Sched, bool ALIGN_EPI = false, bool SP2 = false>
; __device__ __forceinline__ void gemm_phase(PG8_LAS unsigned char* lds, const Gemm g, const Sched& S, const Epi& E) {
;     ...
; #pragma unroll
;         for (int a = 0; a < 2; ++a)
; #pragma unroll
;             for (int b = 0; b < 2; ++b)
; #pragma unroll
;                 for (int m = 0; m < 4; ++m)
; #pragma unroll
;                     for (int n = 0; n < 2; ++n) acc[a][b][m][n] = (f32x4){0.f, 0.f, 0.f, 0.f};
;         cur = nxt; cA = nA; cB = nB; ++ui;
.LBB0_318:
	s_ashr_i32 s17, s16, 31
	s_lshl_b64 s[20:21], s[16:17], 19
	s_add_u32 s20, s34, s20
	s_addc_u32 s21, s35, s21
	s_and_b64 s[22:23], s[2:3], exec
	s_cselect_b32 s13, s21, s25
	s_cselect_b32 s17, s20, s24
	s_ashr_i32 s19, s18, 31
	s_lshl_b64 s[22:23], s[18:19], 19
	s_add_u32 s22, s36, s22
	s_addc_u32 s23, s37, s23
	s_and_b64 s[28:29], s[2:3], exec
	s_cselect_b32 s19, s23, s27
	s_cselect_b32 s42, s22, s26
	s_add_u32 s24, s24, 0x40080
	s_addc_u32 s25, s25, 0
	s_add_u32 s44, s26, 0x100
	v_mov_b64_e32 v[18:19], 0
	v_mov_b64_e32 v[20:21], 0
	v_mov_b64_e32 v[22:23], 0
	v_mov_b64_e32 v[24:25], 0
	v_mov_b64_e32 v[26:27], 0
	v_mov_b64_e32 v[28:29], 0
	v_mov_b64_e32 v[30:31], 0
	v_mov_b64_e32 v[32:33], 0
	v_mov_b64_e32 v[34:35], 0
	v_mov_b64_e32 v[36:37], 0
	v_mov_b64_e32 v[38:39], 0
	v_mov_b64_e32 v[40:41], 0
	v_mov_b64_e32 v[42:43], 0
	v_mov_b64_e32 v[44:45], 0
	v_mov_b64_e32 v[46:47], 0
	v_mov_b64_e32 v[48:49], 0
	v_mov_b64_e32 v[50:51], 0
	v_mov_b64_e32 v[52:53], 0
	v_mov_b64_e32 v[54:55], 0
	v_mov_b64_e32 v[56:57], 0
	v_mov_b64_e32 v[58:59], 0
	v_mov_b64_e32 v[60:61], 0
	v_mov_b64_e32 v[62:63], 0
	v_mov_b64_e32 v[64:65], 0
	v_mov_b64_e32 v[66:67], 0
	v_mov_b64_e32 v[68:69], 0
	v_mov_b64_e32 v[70:71], 0
	v_mov_b64_e32 v[72:73], 0
	v_mov_b64_e32 v[74:75], 0
	v_mov_b64_e32 v[76:77], 0
	v_mov_b64_e32 v[78:79], 0
	v_mov_b64_e32 v[80:81], 0
	v_mov_b64_e32 v[82:83], 0
	v_mov_b64_e32 v[84:85], 0
	v_mov_b64_e32 v[86:87], 0
	v_mov_b64_e32 v[88:89], 0
	v_mov_b64_e32 v[90:91], 0
	v_mov_b64_e32 v[92:93], 0
	v_mov_b64_e32 v[94:95], 0
	v_mov_b64_e32 v[96:97], 0
	v_mov_b64_e32 v[98:99], 0
	v_mov_b64_e32 v[100:101], 0
	v_mov_b64_e32 v[102:103], 0
	v_mov_b64_e32 v[104:105], 0
	v_mov_b64_e32 v[106:107], 0
	v_mov_b64_e32 v[108:109], 0
	v_mov_b64_e32 v[110:111], 0
	v_mov_b64_e32 v[112:113], 0
	v_mov_b64_e32 v[114:115], 0
	v_mov_b64_e32 v[116:117], 0
	v_mov_b64_e32 v[118:119], 0
	v_mov_b64_e32 v[120:121], 0
	v_mov_b64_e32 v[122:123], 0
	v_mov_b64_e32 v[124:125], 0
	v_mov_b64_e32 v[126:127], 0
	v_mov_b64_e32 v[128:129], 0
	v_mov_b64_e32 v[130:131], 0
	v_mov_b64_e32 v[132:133], 0
	v_mov_b64_e32 v[134:135], 0
	v_mov_b64_e32 v[136:137], 0
	v_mov_b64_e32 v[138:139], 0
	v_mov_b64_e32 v[140:141], 0
	v_mov_b64_e32 v[142:143], 0
	v_mov_b64_e32 v[144:145], 0
	s_addc_u32 s45, s27, 0
	s_mov_b32 s52, -2

; #define LAS __attribute__((address_space(3)))
; __global__ void __launch_bounds__(NTHR, 2) hymba_fwd(Args args) {
;     extern __shared__ __attribute__((aligned(16))) unsigned char lds_raw[];
;     LAS unsigned char* lds = (LAS unsigned char*)lds_raw;
;     constexpr int G = 256; const int bx = blockIdx.x; __builtin_assume(bx >= 0 && bx < 256); constexpr int NGW = G * NWAVES, NGT = G * NTHR;
	.amdhsa_kernel _Z9hymba_fwd4Args
		.amdhsa_group_segment_fixed_size 0
		.amdhsa_private_segment_fixed_size 0
		.amdhsa_kernarg_size 432
		.amdhsa_user_sgpr_count 2
		.amdhsa_user_sgpr_dispatch_ptr 0
		.amdhsa_user_sgpr_queue_ptr 0
		.amdhsa_user_sgpr_kernarg_segment_ptr 1
		.amdhsa_user_sgpr_dispatch_id 0
		.amdhsa_user_sgpr_kernarg_preload_length 0
		.amdhsa_user_sgpr_kernarg_preload_offset 0
		.amdhsa_user_sgpr_private_segment_size 0
		.amdhsa_uses_dynamic_stack 0
		.amdhsa_enable_private_segment 0
		.amdhsa_system_sgpr_workgroup_id_x 1
		.amdhsa_system_sgpr_workgroup_id_y 0
		.amdhsa_system_sgpr_workgroup_id_z 0
		.amdhsa_system_sgpr_workgroup_info 0
		.amdhsa_system_vgpr_workitem_id 2
		.amdhsa_next_free_vgpr 256
		.amdhsa_next_free_sgpr 102
		.amdhsa_accum_offset 256
		.amdhsa_reserve_vcc 1
		.amdhsa_float_round_mode_32 0
		.amdhsa_float_round_mode_16_64 0
		.amdhsa_float_denorm_mode_32 3
		.amdhsa_float_denorm_mode_16_64 3
		.amdhsa_dx10_clamp 1
		.amdhsa_ieee_mode 1
		.amdhsa_fp16_overflow 0
		.amdhsa_tg_split 0
		.amdhsa_exception_fp_ieee_invalid_op 0
		.amdhsa_exception_fp_denorm_src 0
		.amdhsa_exception_fp_ieee_div_zero 0
		.amdhsa_exception_fp_ieee_overflow 0
		.amdhsa_exception_fp_ieee_underflow 0
		.amdhsa_exception_fp_ieee_inexact 0
		.amdhsa_exception_int_div_zero 0
	.end_amdhsa_kernel

; #define LAS __attribute__((address_space(3)))
; __global__ void __launch_bounds__(NTHR, 2) hymba_fwd(Args args) {
;     extern __shared__ __attribute__((aligned(16))) unsigned char lds_raw[];
;     LAS unsigned char* lds = (LAS unsigned char*)lds_raw;
;     constexpr int G = 256; const int bx = blockIdx.x; __builtin_assume(bx >= 0 && bx < 256); constexpr int NGW = G * NWAVES, NGT = G * NTHR;
amdhsa.kernels:
  - .agpr_count:     0
    .args:
      - .offset:         0
        .size:           176
        .value_kind:     by_value
      - .offset:         176
        .size:           4
        .value_kind:     hidden_block_count_x
      - .offset:         180
        .size:           4
        .value_kind:     hidden_block_count_y
      - .offset:         184
        .size:           4
        .value_kind:     hidden_block_count_z
      - .offset:         188
        .size:           2
        .value_kind:     hidden_group_size_x
      - .offset:         190
        .size:           2
        .value_kind:     hidden_group_size_y
      - .offset:         192
        .size:           2
        .value_kind:     hidden_group_size_z
      - .offset:         194
        .size:           2
        .value_kind:     hidden_remainder_x
      - .offset:         196
        .size:           2
        .value_kind:     hidden_remainder_y
      - .offset:         198
        .size:           2
        .value_kind:     hidden_remainder_z
      - .offset:         216
        .size:           8
        .value_kind:     hidden_global_offset_x
      - .offset:         224
        .size:           8
        .value_kind:     hidden_global_offset_y
      - .offset:         232
        .size:           8
        .value_kind:     hidden_global_offset_z
      - .offset:         240
        .size:           2
        .value_kind:     hidden_grid_dims
      - .offset:         264
        .size:           8
        .value_kind:     hidden_multigrid_sync_arg
      - .offset:         296
        .size:           4
        .value_kind:     hidden_dynamic_lds_size
    .group_segment_fixed_size: 0
    .kernarg_segment_align: 8
    .kernarg_segment_size: 432
    .language:       OpenCL C
    .language_version:
      - 2
      - 0
    .max_flat_workgroup_size: 512
    .name:           _Z9hymba_fwd4Args
    .private_segment_fixed_size: 0
    .sgpr_count:     108
    .sgpr_spill_count: 4
    .symbol:         _Z9hymba_fwd4Args.kd
    .uniform_work_group_size: 1
    .uses_dynamic_stack: false
    .vgpr_count:     256
    .vgpr_spill_count: 0
    .wavefront_size: 64
